# K/V projection ring of 4 slots
# baseline (speedup 1.0000x reference)
; template <int N> DI void wait_vm() { asm volatile("s_waitcnt vmcnt(%0)" ::"n"(N) : "memory"); }
; DI void raw_barrier() { asm volatile("" ::: "memory"); __builtin_amdgcn_s_barrier(); asm volatile("" ::: "memory"); }
;     ...
;     auto issue_one = [&](int kt, int b, int i) {
;         const int row = lrow + 128 * i;
;         if ((NCH % 512 == 0) || (i < NCH / 512) || row < ROWS) {
;             const int kq = (kt + koff) & (KT - 1);
;             const char* ua = (const char*)A + (size_t)((DBG & 1) ? 0 : kq) * (BM * 64);
;             const char* ub = (const char*)Bt + (size_t)((DBG & 2) ? 0 : kq) * ((size_t)ldbk * 2);
;             const char* src;
;             if (BM % 128 == 0) src = (i < BM / 128) ? (ua + i * 8192 + loff) : (ub + (i * 128 - BM) * 64 + loff);
;             else if (i == 0) src = (lrow < BM) ? (ua + loff) : (ub + loff - BM * 64);
;             else src = ub + (i * 128 - BM) * 64 + loff;
;             __builtin_amdgcn_global_load_lds((const unsigned*)src, (unsigned*)(lds + b * BUF + i * 8192 + tid * 16), 16, 0, 0);
;         }
;     };
;     auto issue = [&](int kt, int b) {
; #pragma unroll
;         for (int i = 0; i < NIT; ++i) issue_one(kt, b, i);
;     };
;     ...
;     __syncthreads();
; #pragma unroll
;     for (int d = 0; d < D; ++d) issue(d, d);
;     int cb = 0, ib = D;
;     for (int kt = 0; kt < KT; ++kt) {
;         if (D > 1 && kt + D - 1 < KT) wait_vm<(D - 1) * NIT>(); else wait_vm<0>();
;         raw_barrier();
;         compute(cb, kt + D < KT, kt + D, ib);
.LBB0_859:
	s_andn2_b64 vcc, exec, s[6:7]
	s_cbranch_vccnz .LBB0_891
	s_bfe_u32 s0, s2, 0x50002
	s_lshr_b32 s1, s3, 7
	s_and_b32 s3, s2, 3
	s_lshl_b32 s6, s0, 18
	v_readlane_b32 s7, v244, 38
	v_mov_b32_e32 v44, v212
	s_add_u32 s8, s7, s6
	v_readlane_b32 s6, v244, 39
	v_mov_b32_e32 v4, v212
	s_addc_u32 s9, s6, 0
	s_lshl_b32 s6, s1, 20
	v_readlane_b32 s7, v243, 18
	s_add_u32 s7, s7, s6
	v_lshrrev_b32_e32 v0, 4, v4
	v_readlane_b32 s10, v243, 19
	v_sub_u32_e32 v0, 0, v0
	s_addc_u32 s11, s10, 0
	s_lshl_b32 s10, s3, 13
	v_xor_b32_e32 v0, v4, v0
	v_lshlrev_b32_e32 v5, 4, v4
	s_add_u32 s10, s7, s10
	v_and_b32_e32 v2, 0xffffffc0, v5
	v_lshlrev_b32_e32 v0, 4, v0
	s_addc_u32 s11, s11, 0
	v_and_or_b32 v0, v0, 48, v2
	v_lshl_add_u64 v[34:35], s[8:9], 0, v[0:1]
	v_lshl_add_u64 v[36:37], s[10:11], 0, v[0:1]
	v_readlane_b32 s8, v243, 25
	v_add_u32_e32 v0, 0, v5
	v_readlane_b32 s9, v243, 26
	v_readfirstlane_b32 s7, v0
	v_add_u32_e32 v5, 0x2000, v0
	v_lshl_add_u64 v[2:3], v[34:35], 0, s[8:9]
	s_mov_b32 m0, s7
	v_readfirstlane_b32 s7, v5
	v_readlane_b32 s8, v243, 5
	s_waitcnt lgkmcnt(0)
	s_barrier
	global_load_lds_dwordx4 v[2:3], off
	v_lshl_add_u64 v[2:3], v[36:37], 0, s[74:75]
	s_mov_b32 m0, s7
	v_readlane_b32 s9, v243, 6
	v_add_u32_e32 v5, 0x4000, v0
	global_load_lds_dwordx4 v[2:3], off
	v_lshl_add_u64 v[2:3], v[34:35], 0, s[8:9]
	v_readfirstlane_b32 s7, v5
	v_readlane_b32 s8, v243, 20
	v_add_u32_e32 v5, 0x6000, v0
	s_mov_b32 m0, s7
	v_readlane_b32 s9, v243, 21
	v_readfirstlane_b32 s7, v5
	global_load_lds_dwordx4 v[2:3], off
	v_lshl_add_u64 v[2:3], v[36:37], 0, s[8:9]
	s_mov_b32 m0, s7
	v_lshlrev_b32_e32 v5, 2, v4
	global_load_lds_dwordx4 v[2:3], off
	v_ashrrev_i32_e32 v2, 6, v4
	v_lshrrev_b32_e32 v3, 30, v2
	v_add_u32_e32 v3, v2, v3
	v_and_b32_e32 v5, 48, v5
	v_ashrrev_i32_e32 v3, 2, v3
	v_sub_u32_e32 v5, 0, v5
	v_mul_i32_i24_e32 v6, 4, v3
	v_bitop3_b32 v5, v4, 48, v5 bitop3:0x48
	v_lshlrev_b32_e32 v4, 6, v4
	v_sub_u32_e32 v2, v2, v6
	v_and_b32_e32 v4, 0x3c0, v4
	v_lshl_or_b32 v40, v2, 11, v4
	v_mov_b32_e32 v2, 0
	s_mov_b32 s9, 2
	s_mov_b32 s7, 0
	v_add_u32_e32 v38, 0, v5
	v_lshl_or_b32 v39, v3, 12, v4
	v_readlane_b32 s8, v243, 27
	s_mov_b32 s10, 0
	v_mov_b32_e32 v3, v2
	v_mov_b32_e32 v4, v2
	v_mov_b32_e32 v5, v2
	v_mov_b32_e32 v6, v2
	v_mov_b32_e32 v7, v2
	v_mov_b32_e32 v8, v2
	v_mov_b32_e32 v9, v2
	v_mov_b32_e32 v10, v2
	v_mov_b32_e32 v11, v2
	v_mov_b32_e32 v12, v2
	v_mov_b32_e32 v13, v2
	v_mov_b32_e32 v14, v2
	v_mov_b32_e32 v15, v2
	v_mov_b32_e32 v16, v2
	v_mov_b32_e32 v17, v2
	v_mov_b32_e32 v18, v2
	v_mov_b32_e32 v19, v2
	v_mov_b32_e32 v20, v2
	v_mov_b32_e32 v21, v2
	v_mov_b32_e32 v22, v2
	v_mov_b32_e32 v23, v2
	v_mov_b32_e32 v24, v2
	v_mov_b32_e32 v25, v2
	v_mov_b32_e32 v26, v2
	v_mov_b32_e32 v27, v2
	v_mov_b32_e32 v28, v2
	v_mov_b32_e32 v29, v2
	v_mov_b32_e32 v30, v2
	v_mov_b32_e32 v31, v2
	v_mov_b32_e32 v32, v2
	v_mov_b32_e32 v33, v2
	v_readfirstlane_b32 s90, v212
	s_nop 3
	s_cmp_lt_u32 s90, 0x100
	s_cbranch_scc0 .Lpkv_c_entry
	v_readfirstlane_b32 s94, v34
	v_readfirstlane_b32 s95, v35
	v_readfirstlane_b32 s92, v36
	v_readfirstlane_b32 s93, v37
	s_nop 3
	s_lshl_b32 s8, s90, 5
	s_lshl_b32 s40, s90, 4
	v_subrev_u32_e32 v227, s94, v34
	v_add_u32_e32 v227, s8, v227
	s_sub_u32 vcc_lo, s94, s40
	s_subb_u32 vcc_hi, s95, 0
	s_sub_u32 s92, s92, s40
	s_subb_u32 s93, s93, 0
	s_mov_b32 s7, 4
	s_mov_b32 s9, 2
	s_lshl_b32 s94, s9, 14
	s_add_u32 s94, s94, s8
	s_mov_b32 m0, s94
	s_add_i32 s40, s59, s7
	s_and_b32 s40, s40, 62
	s_lshl_b32 s94, s40, 12
	s_add_u32 s94, vcc_lo, s94
	s_addc_u32 s95, vcc_hi, 0
	s_lshl_b32 s40, s40, 14
	global_load_lds_dwordx4 v227, s[94:95]
	global_load_lds_dwordx4 v227, s[94:95] offset:1024
	s_add_u32 s94, s92, s40
	s_addc_u32 s95, s93, 0
	s_add_u32 m0, m0, 0x2000
	s_nop 0
	global_load_lds_dwordx4 v227, s[94:95]
	global_load_lds_dwordx4 v227, s[94:95] offset:1024
	s_mov_b32 s7, 6
	s_mov_b32 s9, 3
	s_lshl_b32 s94, s9, 14
	s_add_u32 s94, s94, s8
	s_mov_b32 m0, s94
	s_add_i32 s40, s59, s7
	s_and_b32 s40, s40, 62
	s_lshl_b32 s94, s40, 12
	s_add_u32 s94, vcc_lo, s94
	s_addc_u32 s95, vcc_hi, 0
	s_lshl_b32 s40, s40, 14
	global_load_lds_dwordx4 v227, s[94:95]
	global_load_lds_dwordx4 v227, s[94:95] offset:1024
	s_add_u32 s94, s92, s40
	s_addc_u32 s95, s93, 0
	s_add_u32 m0, m0, 0x2000
	s_nop 0
	global_load_lds_dwordx4 v227, s[94:95]
	global_load_lds_dwordx4 v227, s[94:95] offset:1024
	s_mov_b32 s7, 8
	s_mov_b32 s9, 0
	s_mov_b32 s10, 1
	s_waitcnt vmcnt(10)
	s_barrier
	v_add_u32_e32 v225, v38, v40
	v_add_u32_e32 v224, v38, v39
	ds_read_b128 v[54:57], v224
	ds_read_b128 v[58:61], v224 offset:1024
	ds_read_b128 v[62:65], v224 offset:2048
	ds_read_b128 v[46:49], v225 offset:8192
	ds_read_b128 v[50:53], v225 offset:9216
	ds_read_b128 v[216:219], v224 offset:3072
; DI f32x4 mfma16(bf16x8 a, bf16x8 b, f32x4 c) { return __builtin_amdgcn_mfma_f32_16x16x32_bf16(a, b, c, 0, 0, 0); }
; template <int N> DI void wait_vm() { asm volatile("s_waitcnt vmcnt(%0)" ::"n"(N) : "memory"); }
; DI void raw_barrier() { asm volatile("" ::: "memory"); __builtin_amdgcn_s_barrier(); asm volatile("" ::: "memory"); }
;     ...
;     auto compute = [&](int cb, bool do_issue, int ikt, int ib) {
;         const char* base = lds + cb * BUF;
;         bf16x8 af[MT], bfr[NT];
; #pragma unroll
;         for (int nt = 0; nt < NT; ++nt) {
;             const int br = BM + (nt / NTS) * (BN / NSEG) + wc * (NTS * 16) + (nt % NTS) * 16;
;             bfr[nt] = *(const bf16x8*)(base + (br + l15) * 64 + rsw);
;         }
; #pragma unroll
;         for (int mt = 0; mt < MT; ++mt) af[mt] = *(const bf16x8*)(base + (wr * WM + mt * 16 + l15) * 64 + rsw);
;         constexpr int TOT = MT * NT, PER = (TOT + NIT - 1) / NIT;
; #pragma unroll
;         for (int part = 0; part < NIT; ++part) {
; #pragma unroll
;             for (int q = 0; q < PER; ++q) {
;                 const int idx = part * PER + q;
;                 if (idx < TOT) {
;                     const int mt = idx / NT, nt = idx % NT;
;                     acc[mt][nt] = SWAP ? mfma16(bfr[nt], af[mt], acc[mt][nt]) : mfma16(af[mt], bfr[nt], acc[mt][nt]);
;                 }
;             }
;             __builtin_amdgcn_sched_barrier(0);
;             if (do_issue) issue_one(ikt, ib, part);
;             __builtin_amdgcn_sched_barrier(0);
;         }
;     };
;     __syncthreads();
; #pragma unroll
;     for (int d = 0; d < D; ++d) issue(d, d);
;     int cb = 0, ib = D;
;     for (int kt = 0; kt < KT; ++kt) {
;         if (D > 1 && kt + D - 1 < KT) wait_vm<(D - 1) * NIT>(); else wait_vm<0>();
;         raw_barrier();
;         compute(cb, kt + D < KT, kt + D, ib);
;         cb = (cb + 1 == NST) ? 0 : cb + 1;
;         ib = (ib + 1 == NST) ? 0 : ib + 1;
.Lpkv_l_loop:
	s_lshl_b32 s94, s10, 14
	v_add_u32_e32 v226, s94, v38
	v_add_u32_e32 v225, v226, v40
	v_add_u32_e32 v224, v226, v39
	s_waitcnt lgkmcnt(2)
	v_mfma_f32_16x16x32_bf16 v[30:33], v[46:49], v[54:57], v[30:33]
	s_waitcnt lgkmcnt(1)
	v_mfma_f32_16x16x32_bf16 v[26:29], v[50:53], v[54:57], v[26:29]
	s_waitcnt vmcnt(8) lgkmcnt(0)
	s_barrier
	ds_read_b128 v[54:57], v224
	s_lshl_b32 s94, s9, 14
	s_add_u32 s94, s94, s8
	s_mov_b32 m0, s94
	s_add_i32 s40, s59, s7
	s_and_b32 s40, s40, 62
	s_lshl_b32 s94, s40, 12
	s_add_u32 s94, vcc_lo, s94
	s_addc_u32 s95, vcc_hi, 0
	s_lshl_b32 s40, s40, 14
	global_load_lds_dwordx4 v227, s[94:95]
	global_load_lds_dwordx4 v227, s[94:95] offset:1024
	v_mfma_f32_16x16x32_bf16 v[22:25], v[46:49], v[58:61], v[22:25]
	v_mfma_f32_16x16x32_bf16 v[18:21], v[50:53], v[58:61], v[18:21]
	s_add_u32 s94, s92, s40
	s_addc_u32 s95, s93, 0
	s_add_u32 m0, m0, 0x2000
	s_nop 0
	global_load_lds_dwordx4 v227, s[94:95]
	global_load_lds_dwordx4 v227, s[94:95] offset:1024
	ds_read_b128 v[58:61], v224 offset:1024
	v_mfma_f32_16x16x32_bf16 v[14:17], v[46:49], v[62:65], v[14:17]
	v_mfma_f32_16x16x32_bf16 v[10:13], v[50:53], v[62:65], v[10:13]
	ds_read_b128 v[62:65], v224 offset:2048
	v_mfma_f32_16x16x32_bf16 v[6:9], v[46:49], v[216:219], v[6:9]
	ds_read_b128 v[46:49], v225 offset:8192
	v_mfma_f32_16x16x32_bf16 v[2:5], v[50:53], v[216:219], v[2:5]
	ds_read_b128 v[50:53], v225 offset:9216
	ds_read_b128 v[216:219], v224 offset:3072
	s_add_i32 s10, s10, 1
	s_cmp_lg_u32 s10, 4
	s_cselect_b32 s10, s10, 0
	s_add_i32 s9, s9, 1
	s_cmp_lg_u32 s9, 4
	s_cselect_b32 s9, s9, 0
	s_add_i32 s7, s7, 2
	s_cmp_lg_u32 s7, 64
	s_cbranch_scc1 .Lpkv_l_loop
	s_lshl_b32 s94, s10, 14
	v_add_u32_e32 v226, s94, v38
	v_add_u32_e32 v225, v226, v40
	v_add_u32_e32 v224, v226, v39
	s_waitcnt lgkmcnt(2)
	v_mfma_f32_16x16x32_bf16 v[30:33], v[46:49], v[54:57], v[30:33]
	s_waitcnt lgkmcnt(1)
	v_mfma_f32_16x16x32_bf16 v[26:29], v[50:53], v[54:57], v[26:29]
	s_waitcnt vmcnt(8) lgkmcnt(0)
	s_barrier
	ds_read_b128 v[54:57], v224
	v_mfma_f32_16x16x32_bf16 v[22:25], v[46:49], v[58:61], v[22:25]
	v_mfma_f32_16x16x32_bf16 v[18:21], v[50:53], v[58:61], v[18:21]
	ds_read_b128 v[58:61], v224 offset:1024
	v_mfma_f32_16x16x32_bf16 v[14:17], v[46:49], v[62:65], v[14:17]
	v_mfma_f32_16x16x32_bf16 v[10:13], v[50:53], v[62:65], v[10:13]
	ds_read_b128 v[62:65], v224 offset:2048
	v_mfma_f32_16x16x32_bf16 v[6:9], v[46:49], v[216:219], v[6:9]
	ds_read_b128 v[46:49], v225 offset:8192
	v_mfma_f32_16x16x32_bf16 v[2:5], v[50:53], v[216:219], v[2:5]
	ds_read_b128 v[50:53], v225 offset:9216
	ds_read_b128 v[216:219], v224 offset:3072
	s_add_i32 s10, s10, 1
	s_cmp_lg_u32 s10, 4
	s_cselect_b32 s10, s10, 0
	s_lshl_b32 s94, s10, 14
	v_add_u32_e32 v226, s94, v38
	v_add_u32_e32 v225, v226, v40
	v_add_u32_e32 v224, v226, v39
	s_waitcnt lgkmcnt(2)
	v_mfma_f32_16x16x32_bf16 v[30:33], v[46:49], v[54:57], v[30:33]
	s_waitcnt lgkmcnt(1)
	v_mfma_f32_16x16x32_bf16 v[26:29], v[50:53], v[54:57], v[26:29]
	s_waitcnt vmcnt(4) lgkmcnt(0)
	s_barrier
	ds_read_b128 v[54:57], v224
	v_mfma_f32_16x16x32_bf16 v[22:25], v[46:49], v[58:61], v[22:25]
	v_mfma_f32_16x16x32_bf16 v[18:21], v[50:53], v[58:61], v[18:21]
	ds_read_b128 v[58:61], v224 offset:1024
	v_mfma_f32_16x16x32_bf16 v[14:17], v[46:49], v[62:65], v[14:17]
	v_mfma_f32_16x16x32_bf16 v[10:13], v[50:53], v[62:65], v[10:13]
	ds_read_b128 v[62:65], v224 offset:2048
	v_mfma_f32_16x16x32_bf16 v[6:9], v[46:49], v[216:219], v[6:9]
	ds_read_b128 v[46:49], v225 offset:8192
	v_mfma_f32_16x16x32_bf16 v[2:5], v[50:53], v[216:219], v[2:5]
	ds_read_b128 v[50:53], v225 offset:9216
	ds_read_b128 v[216:219], v224 offset:3072
	s_add_i32 s10, s10, 1
	s_cmp_lg_u32 s10, 4
	s_cselect_b32 s10, s10, 0
	s_lshl_b32 s94, s10, 14
	v_add_u32_e32 v226, s94, v38
	v_add_u32_e32 v225, v226, v40
	v_add_u32_e32 v224, v226, v39
	s_waitcnt lgkmcnt(2)
	v_mfma_f32_16x16x32_bf16 v[30:33], v[46:49], v[54:57], v[30:33]
	s_waitcnt lgkmcnt(1)
	v_mfma_f32_16x16x32_bf16 v[26:29], v[50:53], v[54:57], v[26:29]
	s_waitcnt vmcnt(0) lgkmcnt(0)
	s_barrier
	ds_read_b128 v[54:57], v224
	v_mfma_f32_16x16x32_bf16 v[22:25], v[46:49], v[58:61], v[22:25]
	v_mfma_f32_16x16x32_bf16 v[18:21], v[50:53], v[58:61], v[18:21]
	ds_read_b128 v[58:61], v224 offset:1024
	v_mfma_f32_16x16x32_bf16 v[14:17], v[46:49], v[62:65], v[14:17]
	v_mfma_f32_16x16x32_bf16 v[10:13], v[50:53], v[62:65], v[10:13]
	ds_read_b128 v[62:65], v224 offset:2048
	v_mfma_f32_16x16x32_bf16 v[6:9], v[46:49], v[216:219], v[6:9]
	ds_read_b128 v[46:49], v225 offset:8192
	v_mfma_f32_16x16x32_bf16 v[2:5], v[50:53], v[216:219], v[2:5]
	ds_read_b128 v[50:53], v225 offset:9216
	ds_read_b128 v[216:219], v224 offset:3072
	s_add_i32 s10, s10, 1
	s_cmp_lg_u32 s10, 4
	s_cselect_b32 s10, s10, 0
	s_waitcnt lgkmcnt(2)
	v_mfma_f32_16x16x32_bf16 v[30:33], v[46:49], v[54:57], v[30:33]
	s_waitcnt lgkmcnt(1)
	v_mfma_f32_16x16x32_bf16 v[26:29], v[50:53], v[54:57], v[26:29]
	s_waitcnt lgkmcnt(0)
	v_mfma_f32_16x16x32_bf16 v[22:25], v[46:49], v[58:61], v[22:25]
	v_mfma_f32_16x16x32_bf16 v[18:21], v[50:53], v[58:61], v[18:21]
	v_mfma_f32_16x16x32_bf16 v[14:17], v[46:49], v[62:65], v[14:17]
	v_mfma_f32_16x16x32_bf16 v[10:13], v[50:53], v[62:65], v[10:13]
	v_mfma_f32_16x16x32_bf16 v[6:9], v[46:49], v[216:219], v[6:9]
	v_mfma_f32_16x16x32_bf16 v[2:5], v[50:53], v[216:219], v[2:5]
	s_branch .Lpkv_join
; DI f32x4 mfma16(bf16x8 a, bf16x8 b, f32x4 c) { return __builtin_amdgcn_mfma_f32_16x16x32_bf16(a, b, c, 0, 0, 0); }
; template <int N> DI void wait_vm() { asm volatile("s_waitcnt vmcnt(%0)" ::"n"(N) : "memory"); }
; DI void raw_barrier() { asm volatile("" ::: "memory"); __builtin_amdgcn_s_barrier(); asm volatile("" ::: "memory"); }
;     ...
;     auto compute = [&](int cb, bool do_issue, int ikt, int ib) {
;         const char* base = lds + cb * BUF;
;         bf16x8 af[MT], bfr[NT];
; #pragma unroll
;         for (int nt = 0; nt < NT; ++nt) {
;             const int br = BM + (nt / NTS) * (BN / NSEG) + wc * (NTS * 16) + (nt % NTS) * 16;
;             bfr[nt] = *(const bf16x8*)(base + (br + l15) * 64 + rsw);
;         }
; #pragma unroll
;         for (int mt = 0; mt < MT; ++mt) af[mt] = *(const bf16x8*)(base + (wr * WM + mt * 16 + l15) * 64 + rsw);
;         constexpr int TOT = MT * NT, PER = (TOT + NIT - 1) / NIT;
; #pragma unroll
;         for (int part = 0; part < NIT; ++part) {
; #pragma unroll
;             for (int q = 0; q < PER; ++q) {
;                 const int idx = part * PER + q;
;                 if (idx < TOT) {
;                     const int mt = idx / NT, nt = idx % NT;
;                     acc[mt][nt] = SWAP ? mfma16(bfr[nt], af[mt], acc[mt][nt]) : mfma16(af[mt], bfr[nt], acc[mt][nt]);
;                 }
;             }
;             __builtin_amdgcn_sched_barrier(0);
;             if (do_issue) issue_one(ikt, ib, part);
;             __builtin_amdgcn_sched_barrier(0);
;         }
;     };
;     __syncthreads();
; #pragma unroll
;     for (int d = 0; d < D; ++d) issue(d, d);
;     int cb = 0, ib = D;
;     for (int kt = 0; kt < KT; ++kt) {
;         if (D > 1 && kt + D - 1 < KT) wait_vm<(D - 1) * NIT>(); else wait_vm<0>();
;         raw_barrier();
;         compute(cb, kt + D < KT, kt + D, ib);
;         cb = (cb + 1 == NST) ? 0 : cb + 1;
;         ib = (ib + 1 == NST) ? 0 : ib + 1;
;     }
.Lpkv_c_entry:
	s_mov_b32 s7, 8
	s_mov_b32 s10, 1
	s_waitcnt vmcnt(2)
	s_barrier
	v_add_u32_e32 v225, v38, v40
	v_add_u32_e32 v224, v38, v39
	ds_read_b128 v[54:57], v224
	ds_read_b128 v[58:61], v224 offset:1024
	ds_read_b128 v[62:65], v224 offset:2048
	ds_read_b128 v[46:49], v225 offset:8192
	ds_read_b128 v[50:53], v225 offset:9216
	ds_read_b128 v[216:219], v224 offset:3072
.Lpkv_c_loop:
	s_lshl_b32 s94, s10, 14
	v_add_u32_e32 v226, s94, v38
	v_add_u32_e32 v225, v226, v40
	v_add_u32_e32 v224, v226, v39
	s_waitcnt lgkmcnt(2)
	v_mfma_f32_16x16x32_bf16 v[30:33], v[46:49], v[54:57], v[30:33]
	s_waitcnt lgkmcnt(1)
	v_mfma_f32_16x16x32_bf16 v[26:29], v[50:53], v[54:57], v[26:29]
	s_waitcnt vmcnt(0) lgkmcnt(0)
	s_barrier
	ds_read_b128 v[54:57], v224
	v_mfma_f32_16x16x32_bf16 v[22:25], v[46:49], v[58:61], v[22:25]
	v_mfma_f32_16x16x32_bf16 v[18:21], v[50:53], v[58:61], v[18:21]
	ds_read_b128 v[58:61], v224 offset:1024
	v_mfma_f32_16x16x32_bf16 v[14:17], v[46:49], v[62:65], v[14:17]
	v_mfma_f32_16x16x32_bf16 v[10:13], v[50:53], v[62:65], v[10:13]
	ds_read_b128 v[62:65], v224 offset:2048
	v_mfma_f32_16x16x32_bf16 v[6:9], v[46:49], v[216:219], v[6:9]
	ds_read_b128 v[46:49], v225 offset:8192
	v_mfma_f32_16x16x32_bf16 v[2:5], v[50:53], v[216:219], v[2:5]
	ds_read_b128 v[50:53], v225 offset:9216
	ds_read_b128 v[216:219], v224 offset:3072
	s_add_i32 s10, s10, 1
	s_cmp_lg_u32 s10, 4
	s_cselect_b32 s10, s10, 0
	s_add_i32 s7, s7, 2
	s_cmp_lg_u32 s7, 64
	s_cbranch_scc1 .Lpkv_c_loop
	s_lshl_b32 s94, s10, 14
	v_add_u32_e32 v226, s94, v38
	v_add_u32_e32 v225, v226, v40
	v_add_u32_e32 v224, v226, v39
	s_waitcnt lgkmcnt(2)
	v_mfma_f32_16x16x32_bf16 v[30:33], v[46:49], v[54:57], v[30:33]
	s_waitcnt lgkmcnt(1)
	v_mfma_f32_16x16x32_bf16 v[26:29], v[50:53], v[54:57], v[26:29]
	s_waitcnt vmcnt(0) lgkmcnt(0)
	s_barrier
	ds_read_b128 v[54:57], v224
	v_mfma_f32_16x16x32_bf16 v[22:25], v[46:49], v[58:61], v[22:25]
	v_mfma_f32_16x16x32_bf16 v[18:21], v[50:53], v[58:61], v[18:21]
	ds_read_b128 v[58:61], v224 offset:1024
	v_mfma_f32_16x16x32_bf16 v[14:17], v[46:49], v[62:65], v[14:17]
	v_mfma_f32_16x16x32_bf16 v[10:13], v[50:53], v[62:65], v[10:13]
	ds_read_b128 v[62:65], v224 offset:2048
	v_mfma_f32_16x16x32_bf16 v[6:9], v[46:49], v[216:219], v[6:9]
	ds_read_b128 v[46:49], v225 offset:8192
	v_mfma_f32_16x16x32_bf16 v[2:5], v[50:53], v[216:219], v[2:5]
	ds_read_b128 v[50:53], v225 offset:9216
	ds_read_b128 v[216:219], v224 offset:3072
	s_add_i32 s10, s10, 1
	s_cmp_lg_u32 s10, 4
	s_cselect_b32 s10, s10, 0
	s_lshl_b32 s94, s10, 14
	v_add_u32_e32 v226, s94, v38
	v_add_u32_e32 v225, v226, v40
	v_add_u32_e32 v224, v226, v39
	s_waitcnt lgkmcnt(2)
	v_mfma_f32_16x16x32_bf16 v[30:33], v[46:49], v[54:57], v[30:33]
	s_waitcnt lgkmcnt(1)
	v_mfma_f32_16x16x32_bf16 v[26:29], v[50:53], v[54:57], v[26:29]
	s_waitcnt vmcnt(0) lgkmcnt(0)
	s_barrier
	ds_read_b128 v[54:57], v224
	v_mfma_f32_16x16x32_bf16 v[22:25], v[46:49], v[58:61], v[22:25]
	v_mfma_f32_16x16x32_bf16 v[18:21], v[50:53], v[58:61], v[18:21]
	ds_read_b128 v[58:61], v224 offset:1024
	v_mfma_f32_16x16x32_bf16 v[14:17], v[46:49], v[62:65], v[14:17]
	v_mfma_f32_16x16x32_bf16 v[10:13], v[50:53], v[62:65], v[10:13]
	ds_read_b128 v[62:65], v224 offset:2048
	v_mfma_f32_16x16x32_bf16 v[6:9], v[46:49], v[216:219], v[6:9]
	ds_read_b128 v[46:49], v225 offset:8192
	v_mfma_f32_16x16x32_bf16 v[2:5], v[50:53], v[216:219], v[2:5]
	ds_read_b128 v[50:53], v225 offset:9216
	ds_read_b128 v[216:219], v224 offset:3072
	s_add_i32 s10, s10, 1
	s_cmp_lg_u32 s10, 4
	s_cselect_b32 s10, s10, 0
	s_lshl_b32 s94, s10, 14
	v_add_u32_e32 v226, s94, v38
	v_add_u32_e32 v225, v226, v40
	v_add_u32_e32 v224, v226, v39
	s_waitcnt lgkmcnt(2)
	v_mfma_f32_16x16x32_bf16 v[30:33], v[46:49], v[54:57], v[30:33]
	s_waitcnt lgkmcnt(1)
	v_mfma_f32_16x16x32_bf16 v[26:29], v[50:53], v[54:57], v[26:29]
	s_waitcnt vmcnt(0) lgkmcnt(0)
	s_barrier
	ds_read_b128 v[54:57], v224
	v_mfma_f32_16x16x32_bf16 v[22:25], v[46:49], v[58:61], v[22:25]
	v_mfma_f32_16x16x32_bf16 v[18:21], v[50:53], v[58:61], v[18:21]
	ds_read_b128 v[58:61], v224 offset:1024
	v_mfma_f32_16x16x32_bf16 v[14:17], v[46:49], v[62:65], v[14:17]
	v_mfma_f32_16x16x32_bf16 v[10:13], v[50:53], v[62:65], v[10:13]
	ds_read_b128 v[62:65], v224 offset:2048
	v_mfma_f32_16x16x32_bf16 v[6:9], v[46:49], v[216:219], v[6:9]
	ds_read_b128 v[46:49], v225 offset:8192
	v_mfma_f32_16x16x32_bf16 v[2:5], v[50:53], v[216:219], v[2:5]
	ds_read_b128 v[50:53], v225 offset:9216
	ds_read_b128 v[216:219], v224 offset:3072
	s_add_i32 s10, s10, 1
	s_cmp_lg_u32 s10, 4
	s_cselect_b32 s10, s10, 0
	s_waitcnt lgkmcnt(2)
	v_mfma_f32_16x16x32_bf16 v[30:33], v[46:49], v[54:57], v[30:33]
	s_waitcnt lgkmcnt(1)
	v_mfma_f32_16x16x32_bf16 v[26:29], v[50:53], v[54:57], v[26:29]
	s_waitcnt lgkmcnt(0)
	v_mfma_f32_16x16x32_bf16 v[22:25], v[46:49], v[58:61], v[22:25]
	v_mfma_f32_16x16x32_bf16 v[18:21], v[50:53], v[58:61], v[18:21]
	v_mfma_f32_16x16x32_bf16 v[14:17], v[46:49], v[62:65], v[14:17]
	v_mfma_f32_16x16x32_bf16 v[10:13], v[50:53], v[62:65], v[10:13]
	v_mfma_f32_16x16x32_bf16 v[6:9], v[46:49], v[216:219], v[6:9]
	v_mfma_f32_16x16x32_bf16 v[2:5], v[50:53], v[216:219], v[2:5]
